# c2 + RG-LRU gate weight loads de-serialised (64 dword loads issued together, staged vmcnt waits)
# speedup vs baseline: 1.0107x; 1.0107x over previous
.LBB0_485:
	s_and_b64 vcc, exec, s[4:5]
	s_cbranch_vccz .LBB0_476
	v_mov_b32_e32 v2, s82
	ds_read_b64 v[4:5], v2
	s_lshl_b32 s4, s91, 5
	s_lshr_b32 s7, s91, 1
	s_and_b32 s6, s4, 32
	s_lshl_b32 s4, s68, 3
	s_or_b32 s4, s4, s7
	s_ashr_i32 s5, s4, 31
	s_lshl_b32 s8, s7, 6
	s_lshl_b64 s[4:5], s[4:5], 18
	s_waitcnt lgkmcnt(0)
	v_readfirstlane_b32 s9, v4
	s_lshl_b32 s12, s6, 2
	v_readfirstlane_b32 s11, v5
	s_add_u32 s10, s9, s12
	v_bfe_u32 v121, v114, 4, 2
	v_mov_b32_e32 v2, s83
	s_addc_u32 s11, s11, 0
	v_mov_b32_e32 v61, v3
	s_lshl_b32 s9, s7, 14
	ds_read_b64 v[22:23], v2
	v_lshl_add_u64 v[4:5], s[10:11], 0, v[60:61]
	v_lshl_or_b32 v2, v121, 11, s9
	v_lshl_add_u64 v[18:19], v[4:5], 0, v[2:3]
	v_mov_b32_e32 v27, v3
	v_or_b32_e32 v26, 0x2000, v2
	v_lshl_add_u64 v[4:5], v[4:5], 0, v[26:27]
	s_waitcnt lgkmcnt(0)
	v_readfirstlane_b32 s9, v22
	v_readfirstlane_b32 s11, v23
	s_add_u32 s10, s9, s12
	s_addc_u32 s11, s11, 0
	s_or_b32 s8, s8, s6
	v_mov_b32_e32 v38, s85
	v_mov_b32_e32 v39, s86
	s_lshl_b32 s7, s7, 8
	v_and_b32_e32 v123, 7, v114
	v_mov_b32_e32 v80, v3
	v_mov_b32_e32 v81, v3
	v_mov_b32_e32 v78, v3
	v_mov_b32_e32 v79, v3
	v_mov_b64_e32 v[84:85], v[80:81]
	v_and_b32_e32 v178, -8, v114
	v_mov_b64_e32 v[82:83], v[78:79]
	v_lshl_add_u64 v[46:47], s[10:11], 0, v[60:61]
	v_lshl_add_u64 v[34:35], v[46:47], 0, v[2:3]
	v_lshl_add_u64 v[46:47], v[46:47], 0, v[26:27]
	global_load_dword v6, v[18:19], off
	global_load_dword v86, v[18:19], off offset:256
	global_load_dword v7, v[18:19], off offset:512
	global_load_dword v87, v[18:19], off offset:768
	global_load_dword v8, v[18:19], off offset:1024
	global_load_dword v88, v[18:19], off offset:1280
	global_load_dword v9, v[18:19], off offset:1536
	global_load_dword v89, v[18:19], off offset:1792
	global_load_dword v10, v[4:5], off
	global_load_dword v90, v[4:5], off offset:256
	global_load_dword v11, v[4:5], off offset:512
	global_load_dword v91, v[4:5], off offset:768
	global_load_dword v12, v[4:5], off offset:1024
	global_load_dword v92, v[4:5], off offset:1280
	global_load_dword v13, v[4:5], off offset:1536
	global_load_dword v93, v[4:5], off offset:1792
	global_load_dword v14, v[18:19], off offset:64
	global_load_dword v94, v[18:19], off offset:320
	global_load_dword v15, v[18:19], off offset:576
	global_load_dword v95, v[18:19], off offset:832
	global_load_dword v16, v[18:19], off offset:1088
	global_load_dword v96, v[18:19], off offset:1344
	global_load_dword v17, v[18:19], off offset:1600
	global_load_dword v97, v[18:19], off offset:1856
	global_load_dword v18, v[4:5], off offset:64
	global_load_dword v98, v[4:5], off offset:320
	global_load_dword v19, v[4:5], off offset:576
	global_load_dword v99, v[4:5], off offset:832
	global_load_dword v20, v[4:5], off offset:1088
	global_load_dword v100, v[4:5], off offset:1344
	global_load_dword v21, v[4:5], off offset:1600
	global_load_dword v101, v[4:5], off offset:1856
	global_load_dword v22, v[34:35], off
	global_load_dword v102, v[34:35], off offset:256
	global_load_dword v23, v[34:35], off offset:512
	global_load_dword v103, v[34:35], off offset:768
	global_load_dword v24, v[34:35], off offset:1024
	global_load_dword v104, v[34:35], off offset:1280
	global_load_dword v25, v[34:35], off offset:1536
	global_load_dword v105, v[34:35], off offset:1792
	global_load_dword v26, v[46:47], off
	global_load_dword v106, v[46:47], off offset:256
	global_load_dword v27, v[46:47], off offset:512
	global_load_dword v107, v[46:47], off offset:768
	global_load_dword v28, v[46:47], off offset:1024
	global_load_dword v108, v[46:47], off offset:1280
	global_load_dword v29, v[46:47], off offset:1536
	global_load_dword v109, v[46:47], off offset:1792
	global_load_dword v30, v[34:35], off offset:64
	global_load_dword v110, v[34:35], off offset:320
	global_load_dword v31, v[34:35], off offset:576
	global_load_dword v111, v[34:35], off offset:832
	global_load_dword v32, v[34:35], off offset:1088
	global_load_dword v112, v[34:35], off offset:1344
	global_load_dword v33, v[34:35], off offset:1600
	global_load_dword v113, v[34:35], off offset:1856
	global_load_dword v34, v[46:47], off offset:64
	global_load_dword v48, v[46:47], off offset:320
	global_load_dword v35, v[46:47], off offset:576
	global_load_dword v49, v[46:47], off offset:832
	global_load_dword v36, v[46:47], off offset:1088
	global_load_dword v50, v[46:47], off offset:1344
	global_load_dword v37, v[46:47], off offset:1600
	global_load_dword v51, v[46:47], off offset:1856
	s_waitcnt vmcnt(48)
	v_mul_f32_e32 v6, 0xbfb8aa3b, v6
	v_mul_f32_e32 v86, 0xbfb8aa3b, v86
	v_cvt_pk_bf16_f32 v6, v6, v86
	v_mul_f32_e32 v7, 0xbfb8aa3b, v7
	v_mul_f32_e32 v87, 0xbfb8aa3b, v87
	v_cvt_pk_bf16_f32 v7, v7, v87
	v_mul_f32_e32 v8, 0xbfb8aa3b, v8
	v_mul_f32_e32 v88, 0xbfb8aa3b, v88
	v_cvt_pk_bf16_f32 v8, v8, v88
	v_mul_f32_e32 v9, 0xbfb8aa3b, v9
	v_mul_f32_e32 v89, 0xbfb8aa3b, v89
	v_cvt_pk_bf16_f32 v9, v9, v89
	v_mul_f32_e32 v10, 0xbfb8aa3b, v10
	v_mul_f32_e32 v90, 0xbfb8aa3b, v90
	v_cvt_pk_bf16_f32 v10, v10, v90
	v_mul_f32_e32 v11, 0xbfb8aa3b, v11
	v_mul_f32_e32 v91, 0xbfb8aa3b, v91
	v_cvt_pk_bf16_f32 v11, v11, v91
	v_mul_f32_e32 v12, 0xbfb8aa3b, v12
	v_mul_f32_e32 v92, 0xbfb8aa3b, v92
	v_cvt_pk_bf16_f32 v12, v12, v92
	v_mul_f32_e32 v13, 0xbfb8aa3b, v13
	v_mul_f32_e32 v93, 0xbfb8aa3b, v93
	v_cvt_pk_bf16_f32 v13, v13, v93
	s_waitcnt vmcnt(32)
	v_mul_f32_e32 v14, 0xbfb8aa3b, v14
	v_mul_f32_e32 v94, 0xbfb8aa3b, v94
	v_cvt_pk_bf16_f32 v14, v14, v94
	v_mul_f32_e32 v15, 0xbfb8aa3b, v15
	v_mul_f32_e32 v95, 0xbfb8aa3b, v95
	v_cvt_pk_bf16_f32 v15, v15, v95
	v_mul_f32_e32 v16, 0xbfb8aa3b, v16
	v_mul_f32_e32 v96, 0xbfb8aa3b, v96
	v_cvt_pk_bf16_f32 v16, v16, v96
	v_mul_f32_e32 v17, 0xbfb8aa3b, v17
	v_mul_f32_e32 v97, 0xbfb8aa3b, v97
	v_cvt_pk_bf16_f32 v17, v17, v97
	v_mul_f32_e32 v18, 0xbfb8aa3b, v18
	v_mul_f32_e32 v98, 0xbfb8aa3b, v98
	v_cvt_pk_bf16_f32 v18, v18, v98
	v_mul_f32_e32 v19, 0xbfb8aa3b, v19
	v_mul_f32_e32 v99, 0xbfb8aa3b, v99
	v_cvt_pk_bf16_f32 v19, v19, v99
	v_mul_f32_e32 v20, 0xbfb8aa3b, v20
	v_mul_f32_e32 v100, 0xbfb8aa3b, v100
	v_cvt_pk_bf16_f32 v20, v20, v100
	v_mul_f32_e32 v21, 0xbfb8aa3b, v21
	v_mul_f32_e32 v101, 0xbfb8aa3b, v101
	v_cvt_pk_bf16_f32 v21, v21, v101
	s_waitcnt vmcnt(16)
	v_mul_f32_e32 v22, 0xbfb8aa3b, v22
	v_mul_f32_e32 v102, 0xbfb8aa3b, v102
	v_cvt_pk_bf16_f32 v22, v22, v102
	v_mul_f32_e32 v23, 0xbfb8aa3b, v23
	v_mul_f32_e32 v103, 0xbfb8aa3b, v103
	v_cvt_pk_bf16_f32 v23, v23, v103
	v_mul_f32_e32 v24, 0xbfb8aa3b, v24
	v_mul_f32_e32 v104, 0xbfb8aa3b, v104
	v_cvt_pk_bf16_f32 v24, v24, v104
	v_mul_f32_e32 v25, 0xbfb8aa3b, v25
	v_mul_f32_e32 v105, 0xbfb8aa3b, v105
	v_cvt_pk_bf16_f32 v25, v25, v105
	v_mul_f32_e32 v26, 0xbfb8aa3b, v26
	v_mul_f32_e32 v106, 0xbfb8aa3b, v106
	v_cvt_pk_bf16_f32 v26, v26, v106
	v_mul_f32_e32 v27, 0xbfb8aa3b, v27
	v_mul_f32_e32 v107, 0xbfb8aa3b, v107
	v_cvt_pk_bf16_f32 v27, v27, v107
	v_mul_f32_e32 v28, 0xbfb8aa3b, v28
	v_mul_f32_e32 v108, 0xbfb8aa3b, v108
	v_cvt_pk_bf16_f32 v28, v28, v108
	v_mul_f32_e32 v29, 0xbfb8aa3b, v29
	v_mul_f32_e32 v109, 0xbfb8aa3b, v109
	v_cvt_pk_bf16_f32 v29, v29, v109
	s_waitcnt vmcnt(0)
	v_mul_f32_e32 v30, 0xbfb8aa3b, v30
	v_mul_f32_e32 v110, 0xbfb8aa3b, v110
	v_cvt_pk_bf16_f32 v30, v30, v110
	v_mul_f32_e32 v31, 0xbfb8aa3b, v31
	v_mul_f32_e32 v111, 0xbfb8aa3b, v111
	v_cvt_pk_bf16_f32 v31, v31, v111
	v_mul_f32_e32 v32, 0xbfb8aa3b, v32
	v_mul_f32_e32 v112, 0xbfb8aa3b, v112
	v_cvt_pk_bf16_f32 v32, v32, v112
	v_mul_f32_e32 v33, 0xbfb8aa3b, v33
	v_mul_f32_e32 v113, 0xbfb8aa3b, v113
	v_cvt_pk_bf16_f32 v33, v33, v113
	v_mul_f32_e32 v34, 0xbfb8aa3b, v34
	v_mul_f32_e32 v48, 0xbfb8aa3b, v48
	v_cvt_pk_bf16_f32 v34, v34, v48
	v_mul_f32_e32 v35, 0xbfb8aa3b, v35
	v_mul_f32_e32 v49, 0xbfb8aa3b, v49
	v_cvt_pk_bf16_f32 v35, v35, v49
	v_mul_f32_e32 v36, 0xbfb8aa3b, v36
	v_mul_f32_e32 v50, 0xbfb8aa3b, v50
	v_cvt_pk_bf16_f32 v36, v36, v50
	v_mul_f32_e32 v37, 0xbfb8aa3b, v37
	v_mul_f32_e32 v51, 0xbfb8aa3b, v51
	v_cvt_pk_bf16_f32 v37, v37, v51
	v_or_b32_e32 v2, s8, v115
	v_lshlrev_b32_e32 v44, 2, v2
	v_mov_b32_e32 v5, s84
	v_or_b32_e32 v40, 64, v44
	v_lshlrev_b32_e32 v2, 5, v123
	ds_read_b64 v[4:5], v5
	ds_read_b64 v[42:43], v38
	global_load_dword v124, v40, s[2:3]
	ds_read2_b64 v[38:41], v39 offset1:1
	s_waitcnt lgkmcnt(2)
	v_readfirstlane_b32 s8, v4
	v_readfirstlane_b32 s9, v5
	s_waitcnt lgkmcnt(1)
	v_readfirstlane_b32 s10, v42
	s_waitcnt lgkmcnt(0)
	v_readfirstlane_b32 s12, v38
	v_readfirstlane_b32 s11, v43
	v_readfirstlane_b32 s13, v39
	global_load_dword v118, v44, s[8:9]
	s_nop 2
	global_load_dword v122, v44, s[10:11]
	global_load_dword v125, v44, s[10:11] offset:64
	global_load_dword v126, v44, s[8:9] offset:64
	global_load_dword v127, v44, s[2:3]
	s_add_u32 s8, s12, s7
	s_addc_u32 s9, s13, 0
	v_lshl_add_u64 v[4:5], s[8:9], 0, v[2:3]
	v_readfirstlane_b32 s14, v40
	v_add_co_u32_e32 v62, vcc, s87, v4
	v_readfirstlane_b32 s15, v41
	s_add_u32 s10, s14, s7
	v_lshl_add_u64 v[58:59], v[4:5], 0, s[64:65]
	v_addc_co_u32_e32 v63, vcc, 0, v5, vcc
	global_load_dwordx4 v[38:41], v2, s[8:9] offset:16
	global_load_dwordx4 v[42:45], v2, s[8:9]
	global_load_dwordx4 v[46:49], v2, s[8:9] offset:2064
	global_load_dwordx4 v[50:53], v2, s[8:9] offset:2048
	s_addc_u32 s11, s15, 0
	v_lshl_add_u64 v[4:5], v[4:5], 0, s[66:67]
	global_load_dwordx4 v[54:57], v[62:63], off
	s_nop 0
	global_load_dwordx4 v[58:61], v[58:59], off offset:16
	s_nop 0
	global_load_dwordx4 v[62:65], v[62:63], off offset:2048
	s_nop 0
	global_load_dwordx4 v[66:69], v[4:5], off offset:16
	global_load_dwordx4 v[70:73], v2, s[10:11] offset:16
	global_load_dwordx4 v[74:77], v2, s[10:11]
	s_add_u32 s4, s72, s4
	s_addc_u32 s5, s73, s5
	v_lshlrev_b32_e32 v2, 4, v123
	v_lshl_add_u64 v[180:181], s[4:5], 0, v[2:3]
	v_cmp_lt_i32_e32 vcc, 7, v114
	s_and_saveexec_b64 s[4:5], vcc
	s_cbranch_execz .LBB0_488
	v_add_u32_e32 v2, -3, v178
	v_lshlrev_b64 v[4:5], 7, v[2:3]
	v_lshl_add_u64 v[4:5], v[180:181], 0, v[4:5]
	global_load_dwordx4 v[82:85], v[4:5], off nt
